# pool-GEMM residual epilogue: first batch retired with counted vmcnt per row group; out-proj K-loop preheader blanket vmcnt(0) removed
# speedup vs baseline: 1.0026x; 1.0026x over previous
; #define PG8_STAGE(bufoff, gbase, voff) do { _Pragma("unroll") for (int _i = 0; _i < 2; ++_i) \
;         __builtin_amdgcn_global_load_lds((const unsigned*)((const char*)(gbase) + (voff)[_i]), (LAS unsigned*)(lds + (bufoff) + ldsw + _i * 8192), 16, 0, 0); } while (0)
; #define PG8_LDA(dst, b, h) do { _Pragma("unroll") for (int m = 0; m < 4; ++m) _Pragma("unroll") for (int k = 0; k < 2; ++k) dst[m][k] = *(const LAS bf16x8*)(lds + PG8_SA(b, h) + aoff + m * 2048 + k * 1024); } while (0)
; #define PG8_LDB(dst, b, h) do { _Pragma("unroll") for (int n = 0; n < 2; ++n) _Pragma("unroll") for (int k = 0; k < 2; ++k) dst[n][k] = *(const LAS bf16x8*)(lds + PG8_SB(b, h) + boff + n * 2048 + k * 1024); } while (0)
; #define PG8_MMA(ai, bj, At, Bt) do { __builtin_amdgcn_s_setprio(1); _Pragma("unroll") for (int m = 0; m < 4; ++m) _Pragma("unroll") for (int n = 0; n < 2; ++n) _Pragma("unroll") for (int k = 0; k < 2; ++k) \
;         acc[ai][bj][m][n] = __builtin_amdgcn_mfma_f32_16x16x32_bf16(Bt[n][k], At[m][k], acc[ai][bj][m][n], 0, 0, 0); __builtin_amdgcn_s_setprio(0); } while (0)
; #define PG8_WAIT_V(n) asm volatile("s_waitcnt vmcnt(" #n ")" ::: "memory")
; #define PG8_WAIT_L(n) asm volatile("s_waitcnt lgkmcnt(" #n ")" ::: "memory")
; #define PG8_BAR __builtin_amdgcn_s_barrier()
; template <class Epi, bool ALIGN_EPI>
; __device__ __forceinline__ void gemm_phase(LAS unsigned char* lds, const Gemm g, int G, int cid, const Epi& E) {
;     ...
;         const char* nA = has_next ? tileA(g, nxt) : cA; const char* nB = has_next ? tileB(g, nxt) : cB;
;         for (int t = 0; t < nt; t += 2) {
;             const bool last = (t == nt - 2);
;             const char* a1 = cA + (size_t)(t + 1) * kA;
;             const char* a2 = last ? nA : cA + (size_t)(t + 2) * kA; const char* b2 = last ? nB : cB + (size_t)(t + 2) * kB;
;             const char* a3 = a2 + kA; const char* b3 = b2 + kB;
;             PG8_LDB(B0, 0, 0); PG8_LDB(B1, 0, 1); PG8_SCHED; PG8_LDA(At, 0, 0); PG8_STAGE(PG8_SA(1, 1), a1 + hA, voffA);
;             PG8_WAIT_V(8); PG8_WAIT_L(0); PG8_BAR; PG8_MMA(0, 0, At, B0); PG8_MMA(0, 1, At, B1); PG8_BAR; PG8_SCHED;
;             PG8_LDA(At, 0, 1); PG8_STAGE(PG8_SB(0, 0), b2, voffB); PG8_STAGE(PG8_SB(0, 1), b2 + hB, voffB); PG8_STAGE(PG8_SA(0, 0), a2, voffA);
;             PG8_WAIT_V(8); PG8_WAIT_L(0); PG8_BAR; PG8_MMA(1, 0, At, B0); PG8_MMA(1, 1, At, B1); PG8_BAR; PG8_SCHED;
.LBB0_169:
	s_add_u32 s44, s50, 0x100
	s_addc_u32 s45, s51, 0
	s_add_i32 s6, 0, 0x10000
	s_cmp_eq_u32 s79, 4
	s_cselect_b32 s55, s43, s45
	s_cselect_b32 s54, s42, s44
	s_cselect_b32 s53, s30, s78
	s_cselect_b32 s52, s76, s77
	s_add_i32 s86, 0, 0x14000
	v_add_u32_e32 v84, s6, v212
	v_add_u32_e32 v100, s86, v212
	ds_read_b128 v[68:71], v84
	ds_read_b128 v[76:79], v84 offset:1024
	ds_read_b128 v[80:83], v84 offset:2048
	ds_read_b128 v[84:87], v84 offset:3072
	ds_read_b128 v[88:91], v100
	ds_read_b128 v[92:95], v100 offset:1024
	ds_read_b128 v[96:99], v100 offset:2048
	ds_read_b128 v[100:103], v100 offset:3072
	v_lshl_add_u64 v[198:199], s[50:51], 0, v[184:185]
	s_add_i32 m0, s24, 0xc000
	ds_read_b128 v[164:167], v214
	ds_read_b128 v[168:171], v214 offset:1024
	ds_read_b128 v[172:175], v214 offset:2048
	ds_read_b128 v[176:179], v214 offset:3072
	ds_read_b128 v[188:191], v214 offset:4096
	ds_read_b128 v[206:209], v214 offset:5120
	ds_read_b128 v[216:219], v214 offset:6144
	ds_read_b128 v[220:223], v214 offset:7168
	global_load_lds_dwordx4 v[198:199], off
	v_lshl_add_u64 v[198:199], s[50:51], 0, v[186:187]
	s_add_i32 m0, s24, 0xe000
	s_nop 0
	global_load_lds_dwordx4 v[198:199], off
	s_waitcnt vmcnt(8)
	s_waitcnt lgkmcnt(0)
	s_barrier
	s_setprio 1
	s_waitcnt lgkmcnt(0)
	v_mfma_f32_16x16x32_bf16 v[160:163], v[68:71], v[164:167], v[160:163]
	v_mfma_f32_16x16x32_bf16 v[156:159], v[80:83], v[164:167], v[156:159]
	v_mfma_f32_16x16x32_bf16 v[144:147], v[68:71], v[172:175], v[144:147]
	v_mfma_f32_16x16x32_bf16 v[140:143], v[80:83], v[172:175], v[140:143]
	v_mfma_f32_16x16x32_bf16 v[124:127], v[68:71], v[188:191], v[124:127]
	v_mfma_f32_16x16x32_bf16 v[120:123], v[80:83], v[188:191], v[120:123]
	v_mfma_f32_16x16x32_bf16 v[108:111], v[68:71], v[216:219], v[108:111]
	v_mfma_f32_16x16x32_bf16 v[104:107], v[80:83], v[216:219], v[104:107]
	v_mfma_f32_16x16x32_bf16 v[160:163], v[76:79], v[168:171], v[160:163]
	v_mfma_f32_16x16x32_bf16 v[156:159], v[84:87], v[168:171], v[156:159]
	v_mfma_f32_16x16x32_bf16 v[144:147], v[76:79], v[176:179], v[144:147]
	v_mfma_f32_16x16x32_bf16 v[140:143], v[84:87], v[176:179], v[140:143]
	v_mfma_f32_16x16x32_bf16 v[124:127], v[76:79], v[206:209], v[124:127]
	v_mfma_f32_16x16x32_bf16 v[120:123], v[84:87], v[206:209], v[120:123]
	v_mfma_f32_16x16x32_bf16 v[108:111], v[76:79], v[220:223], v[108:111]
	v_mfma_f32_16x16x32_bf16 v[104:107], v[84:87], v[220:223], v[104:107]
	s_setprio 0
	s_setprio 1
	v_mfma_f32_16x16x32_bf16 v[152:155], v[88:91], v[164:167], v[152:155]
	v_mfma_f32_16x16x32_bf16 v[148:151], v[96:99], v[164:167], v[148:151]
	v_mfma_f32_16x16x32_bf16 v[132:135], v[88:91], v[172:175], v[132:135]
	v_mfma_f32_16x16x32_bf16 v[128:131], v[96:99], v[172:175], v[128:131]
	v_mfma_f32_16x16x32_bf16 v[116:119], v[88:91], v[188:191], v[116:119]
	v_mfma_f32_16x16x32_bf16 v[112:115], v[96:99], v[188:191], v[112:115]
	v_mfma_f32_16x16x32_bf16 v[72:75], v[88:91], v[216:219], v[72:75]
	v_mfma_f32_16x16x32_bf16 v[64:67], v[96:99], v[216:219], v[64:67]
	v_mfma_f32_16x16x32_bf16 v[152:155], v[92:95], v[168:171], v[152:155]
	v_mfma_f32_16x16x32_bf16 v[148:151], v[100:103], v[168:171], v[148:151]
	v_mfma_f32_16x16x32_bf16 v[132:135], v[92:95], v[176:179], v[132:135]
	v_mfma_f32_16x16x32_bf16 v[128:131], v[100:103], v[176:179], v[128:131]
	v_mfma_f32_16x16x32_bf16 v[116:119], v[92:95], v[206:209], v[116:119]
	v_mfma_f32_16x16x32_bf16 v[112:115], v[100:103], v[206:209], v[112:115]
	v_mfma_f32_16x16x32_bf16 v[72:75], v[92:95], v[220:223], v[72:75]
	v_mfma_f32_16x16x32_bf16 v[64:67], v[100:103], v[220:223], v[64:67]
	s_setprio 0
	s_barrier
	s_add_i32 s6, s6, s23
	v_lshl_add_u64 v[198:199], s[52:53], 0, v[138:139]
	s_mov_b32 m0, s6
	ds_read_b128 v[164:167], v214 offset:16384
	ds_read_b128 v[168:171], v214 offset:17408
	ds_read_b128 v[172:175], v214 offset:18432
	ds_read_b128 v[176:179], v214 offset:19456
	ds_read_b128 v[188:191], v214 offset:20480
	ds_read_b128 v[206:209], v214 offset:21504
	ds_read_b128 v[216:219], v214 offset:22528
	ds_read_b128 v[220:223], v214 offset:23552
	global_load_lds_dwordx4 v[198:199], off
	s_add_i32 m0, s6, 0x2000
	s_add_u32 s6, s52, 0x2000
	v_lshl_add_u64 v[198:199], s[52:53], 0, v[136:137]
	s_addc_u32 s7, s53, 0
	s_add_i32 s50, s86, s23
	global_load_lds_dwordx4 v[198:199], off
	v_lshl_add_u64 v[198:199], s[6:7], 0, v[138:139]
	s_mov_b32 m0, s50
	v_lshl_add_u64 v[200:201], s[54:55], 0, v[180:181]
	global_load_lds_dwordx4 v[198:199], off
	v_lshl_add_u64 v[198:199], s[6:7], 0, v[136:137]
	s_add_i32 m0, s50, 0x2000
	s_nop 0
	global_load_lds_dwordx4 v[198:199], off
	v_lshl_add_u64 v[198:199], s[54:55], 0, v[182:183]
	s_mov_b32 m0, s24
	s_nop 0
	global_load_lds_dwordx4 v[198:199], off
	s_mov_b32 m0, s25
	s_nop 0
	global_load_lds_dwordx4 v[200:201], off
	s_waitcnt vmcnt(8)
	s_waitcnt lgkmcnt(0)
	s_barrier
; #define PG8_STAGE(bufoff, gbase, voff) do { _Pragma("unroll") for (int _i = 0; _i < 2; ++_i) \
;         __builtin_amdgcn_global_load_lds((const unsigned*)((const char*)(gbase) + (voff)[_i]), (LAS unsigned*)(lds + (bufoff) + ldsw + _i * 8192), 16, 0, 0); } while (0)
; #define PG8_LDA(dst, b, h) do { _Pragma("unroll") for (int m = 0; m < 4; ++m) _Pragma("unroll") for (int k = 0; k < 2; ++k) dst[m][k] = *(const LAS bf16x8*)(lds + PG8_SA(b, h) + aoff + m * 2048 + k * 1024); } while (0)
; #define PG8_LDB(dst, b, h) do { _Pragma("unroll") for (int n = 0; n < 2; ++n) _Pragma("unroll") for (int k = 0; k < 2; ++k) dst[n][k] = *(const LAS bf16x8*)(lds + PG8_SB(b, h) + boff + n * 2048 + k * 1024); } while (0)
; #define PG8_MMA(ai, bj, At, Bt) do { __builtin_amdgcn_s_setprio(1); _Pragma("unroll") for (int m = 0; m < 4; ++m) _Pragma("unroll") for (int n = 0; n < 2; ++n) _Pragma("unroll") for (int k = 0; k < 2; ++k) \
;         acc[ai][bj][m][n] = __builtin_amdgcn_mfma_f32_16x16x32_bf16(Bt[n][k], At[m][k], acc[ai][bj][m][n], 0, 0, 0); __builtin_amdgcn_s_setprio(0); } while (0)
; #define PG8_WAIT_V(n) asm volatile("s_waitcnt vmcnt(" #n ")" ::: "memory")
; #define PG8_WAIT_L(n) asm volatile("s_waitcnt lgkmcnt(" #n ")" ::: "memory")
; #define PG8_BAR __builtin_amdgcn_s_barrier()
; #define PG8_SCHED __builtin_amdgcn_sched_barrier(0)
; template <class Epi, bool ALIGN_EPI>
; __device__ __forceinline__ void gemm_phase(LAS unsigned char* lds, const Gemm g, int G, int cid, const Epi& E) {
;     ...
;             PG8_WAIT_V(8); PG8_WAIT_L(0); PG8_BAR; PG8_MMA(1, 0, At, B0); PG8_MMA(1, 1, At, B1); PG8_BAR; PG8_SCHED;
;             PG8_LDB(B0, 1, 0); PG8_LDB(B1, 1, 1); PG8_SCHED; PG8_LDA(At, 1, 0); PG8_STAGE(PG8_SA(0, 1), a2 + hA, voffA);
;             PG8_WAIT_V(8); PG8_WAIT_L(0); PG8_BAR; PG8_MMA(0, 0, At, B0); PG8_MMA(0, 1, At, B1); PG8_BAR; PG8_SCHED;
	s_setprio 1
	s_waitcnt lgkmcnt(0)
	v_mfma_f32_16x16x32_bf16 v[60:63], v[68:71], v[164:167], v[60:63]
	v_mfma_f32_16x16x32_bf16 v[56:59], v[80:83], v[164:167], v[56:59]
	v_mfma_f32_16x16x32_bf16 v[44:47], v[68:71], v[172:175], v[44:47]
	v_mfma_f32_16x16x32_bf16 v[40:43], v[80:83], v[172:175], v[40:43]
	v_mfma_f32_16x16x32_bf16 v[28:31], v[68:71], v[188:191], v[28:31]
	v_mfma_f32_16x16x32_bf16 v[24:27], v[80:83], v[188:191], v[24:27]
	v_mfma_f32_16x16x32_bf16 v[12:15], v[68:71], v[216:219], v[12:15]
	v_mfma_f32_16x16x32_bf16 v[8:11], v[80:83], v[216:219], v[8:11]
	v_mfma_f32_16x16x32_bf16 v[60:63], v[76:79], v[168:171], v[60:63]
	v_mfma_f32_16x16x32_bf16 v[56:59], v[84:87], v[168:171], v[56:59]
	v_mfma_f32_16x16x32_bf16 v[44:47], v[76:79], v[176:179], v[44:47]
	v_mfma_f32_16x16x32_bf16 v[40:43], v[84:87], v[176:179], v[40:43]
	v_mfma_f32_16x16x32_bf16 v[28:31], v[76:79], v[206:209], v[28:31]
	v_mfma_f32_16x16x32_bf16 v[24:27], v[84:87], v[206:209], v[24:27]
	v_mfma_f32_16x16x32_bf16 v[12:15], v[76:79], v[220:223], v[12:15]
	v_mfma_f32_16x16x32_bf16 v[8:11], v[84:87], v[220:223], v[8:11]
	s_setprio 0
	s_setprio 1
	v_mfma_f32_16x16x32_bf16 v[52:55], v[88:91], v[164:167], v[52:55]
	v_mfma_f32_16x16x32_bf16 v[48:51], v[96:99], v[164:167], v[48:51]
	v_mfma_f32_16x16x32_bf16 v[36:39], v[88:91], v[172:175], v[36:39]
	v_mfma_f32_16x16x32_bf16 v[32:35], v[96:99], v[172:175], v[32:35]
	v_mfma_f32_16x16x32_bf16 v[20:23], v[88:91], v[188:191], v[20:23]
	v_mfma_f32_16x16x32_bf16 v[16:19], v[96:99], v[188:191], v[16:19]
	v_mfma_f32_16x16x32_bf16 v[4:7], v[88:91], v[216:219], v[4:7]
	v_mfma_f32_16x16x32_bf16 v[0:3], v[96:99], v[216:219], v[0:3]
	v_mfma_f32_16x16x32_bf16 v[52:55], v[92:95], v[168:171], v[52:55]
	v_mfma_f32_16x16x32_bf16 v[48:51], v[100:103], v[168:171], v[48:51]
	v_mfma_f32_16x16x32_bf16 v[36:39], v[92:95], v[176:179], v[36:39]
	v_mfma_f32_16x16x32_bf16 v[32:35], v[100:103], v[176:179], v[32:35]
	v_mfma_f32_16x16x32_bf16 v[20:23], v[92:95], v[206:209], v[20:23]
	v_mfma_f32_16x16x32_bf16 v[16:19], v[100:103], v[206:209], v[16:19]
	v_mfma_f32_16x16x32_bf16 v[4:7], v[92:95], v[220:223], v[4:7]
	v_mfma_f32_16x16x32_bf16 v[0:3], v[100:103], v[220:223], v[0:3]
	s_setprio 0
	s_barrier
	s_add_i32 s50, 0, 0x18000
	s_add_i32 s51, 0, 0x1c000
	v_add_u32_e32 v84, s50, v212
	v_add_u32_e32 v100, s51, v212
	ds_read_b128 v[68:71], v84
	ds_read_b128 v[76:79], v84 offset:1024
	ds_read_b128 v[80:83], v84 offset:2048
	ds_read_b128 v[84:87], v84 offset:3072
	ds_read_b128 v[88:91], v100
	ds_read_b128 v[92:95], v100 offset:1024
	ds_read_b128 v[96:99], v100 offset:2048
	ds_read_b128 v[100:103], v100 offset:3072
	s_add_u32 s6, s54, 0x84000
	s_addc_u32 s7, s55, 0
	s_mov_b32 m0, s56
	v_lshl_add_u64 v[210:211], s[6:7], 0, v[182:183]
	ds_read_b128 v[164:167], v214 offset:32768
	ds_read_b128 v[168:171], v214 offset:33792
	ds_read_b128 v[172:175], v214 offset:34816
	ds_read_b128 v[176:179], v214 offset:35840
	ds_read_b128 v[188:191], v214 offset:36864
	ds_read_b128 v[206:209], v214 offset:37888
	ds_read_b128 v[216:219], v214 offset:38912
	ds_read_b128 v[220:223], v214 offset:39936
	global_load_lds_dwordx4 v[210:211], off
	v_lshl_add_u64 v[210:211], s[6:7], 0, v[180:181]
	s_mov_b32 m0, s57
	s_nop 0
	global_load_lds_dwordx4 v[210:211], off
	s_waitcnt vmcnt(8)
	s_waitcnt lgkmcnt(0)
	s_barrier
	s_setprio 1
	s_waitcnt lgkmcnt(0)
	v_mfma_f32_16x16x32_bf16 v[160:163], v[68:71], v[164:167], v[160:163]
	v_mfma_f32_16x16x32_bf16 v[156:159], v[80:83], v[164:167], v[156:159]
	v_mfma_f32_16x16x32_bf16 v[144:147], v[68:71], v[172:175], v[144:147]
	v_mfma_f32_16x16x32_bf16 v[140:143], v[80:83], v[172:175], v[140:143]
	v_mfma_f32_16x16x32_bf16 v[124:127], v[68:71], v[188:191], v[124:127]
	v_mfma_f32_16x16x32_bf16 v[120:123], v[80:83], v[188:191], v[120:123]
	v_mfma_f32_16x16x32_bf16 v[108:111], v[68:71], v[216:219], v[108:111]
	v_mfma_f32_16x16x32_bf16 v[104:107], v[80:83], v[216:219], v[104:107]
	v_mfma_f32_16x16x32_bf16 v[160:163], v[76:79], v[168:171], v[160:163]
	v_mfma_f32_16x16x32_bf16 v[156:159], v[84:87], v[168:171], v[156:159]
	v_mfma_f32_16x16x32_bf16 v[144:147], v[76:79], v[176:179], v[144:147]
	v_mfma_f32_16x16x32_bf16 v[140:143], v[84:87], v[176:179], v[140:143]
	v_mfma_f32_16x16x32_bf16 v[124:127], v[76:79], v[206:209], v[124:127]
	v_mfma_f32_16x16x32_bf16 v[120:123], v[84:87], v[206:209], v[120:123]
	v_mfma_f32_16x16x32_bf16 v[108:111], v[76:79], v[220:223], v[108:111]
	v_mfma_f32_16x16x32_bf16 v[104:107], v[84:87], v[220:223], v[104:107]
	s_setprio 0
	s_setprio 1
	v_mfma_f32_16x16x32_bf16 v[152:155], v[88:91], v[164:167], v[152:155]
	v_mfma_f32_16x16x32_bf16 v[148:151], v[96:99], v[164:167], v[148:151]
	v_mfma_f32_16x16x32_bf16 v[132:135], v[88:91], v[172:175], v[132:135]
	v_mfma_f32_16x16x32_bf16 v[128:131], v[96:99], v[172:175], v[128:131]
	v_mfma_f32_16x16x32_bf16 v[116:119], v[88:91], v[188:191], v[116:119]
	v_mfma_f32_16x16x32_bf16 v[112:115], v[96:99], v[188:191], v[112:115]
	v_mfma_f32_16x16x32_bf16 v[72:75], v[88:91], v[216:219], v[72:75]
	v_mfma_f32_16x16x32_bf16 v[64:67], v[96:99], v[216:219], v[64:67]
	v_mfma_f32_16x16x32_bf16 v[152:155], v[92:95], v[168:171], v[152:155]
	v_mfma_f32_16x16x32_bf16 v[148:151], v[100:103], v[168:171], v[148:151]
	v_mfma_f32_16x16x32_bf16 v[132:135], v[92:95], v[176:179], v[132:135]
	v_mfma_f32_16x16x32_bf16 v[128:131], v[100:103], v[176:179], v[128:131]
	v_mfma_f32_16x16x32_bf16 v[116:119], v[92:95], v[206:209], v[116:119]
	v_mfma_f32_16x16x32_bf16 v[112:115], v[100:103], v[206:209], v[112:115]
	v_mfma_f32_16x16x32_bf16 v[72:75], v[92:95], v[220:223], v[72:75]
	v_mfma_f32_16x16x32_bf16 v[64:67], v[100:103], v[220:223], v[64:67]
	s_setprio 0
	s_barrier
; #define PG8_STAGE(bufoff, gbase, voff) do { _Pragma("unroll") for (int _i = 0; _i < 2; ++_i) \
;         __builtin_amdgcn_global_load_lds((const unsigned*)((const char*)(gbase) + (voff)[_i]), (LAS unsigned*)(lds + (bufoff) + ldsw + _i * 8192), 16, 0, 0); } while (0)
; #define PG8_LDA(dst, b, h) do { _Pragma("unroll") for (int m = 0; m < 4; ++m) _Pragma("unroll") for (int k = 0; k < 2; ++k) dst[m][k] = *(const LAS bf16x8*)(lds + PG8_SA(b, h) + aoff + m * 2048 + k * 1024); } while (0)
; #define PG8_WAIT_V(n) asm volatile("s_waitcnt vmcnt(" #n ")" ::: "memory")
; #define PG8_WAIT_L(n) asm volatile("s_waitcnt lgkmcnt(" #n ")" ::: "memory")
; #define PG8_BAR __builtin_amdgcn_s_barrier()
; #define PG8_SCHED __builtin_amdgcn_sched_barrier(0)
; template <class Epi, bool ALIGN_EPI>
; __device__ __forceinline__ void gemm_phase(LAS unsigned char* lds, const Gemm g, int G, int cid, const Epi& E) {
;     ...
;             PG8_LDA(At, 1, 1); PG8_STAGE(PG8_SB(1, 0), b3, voffB); PG8_STAGE(PG8_SB(1, 1), b3 + hB, voffB); PG8_STAGE(PG8_SA(1, 0), a3, voffA);
;             PG8_WAIT_V(8); PG8_WAIT_L(0); PG8_BAR; PG8_MMA(1, 0, At, B0); PG8_MMA(1, 1, At, B1); PG8_BAR; PG8_SCHED;
;     __device__ __forceinline__ void operator()(const f32x4 (&acc)[2][2][4][2], const Unit& u, int wr, int wc, int fr, int fq, const LAS float*) const {
;         const int row0 = u.pm * BM + wr * 64 + fr, col0 = u.pn * BM + wc * 32 + 8 * fq;
;         f32x4 bv[2][2], sv[2][2];
; #pragma unroll
;         for (int bj = 0; bj < 2; ++bj)
; #pragma unroll
;             for (int n = 0; n < 2; ++n) { bv[bj][n] = HB ? *(const f32x4*)(bias + col0 + bj * HALF + 4 * n) : (f32x4){0.f, 0.f, 0.f, 0.f};
;                                            sv[bj][n] = HB ? *(const f32x4*)(scale + col0 + bj * HALF + 4 * n) : (f32x4){1.f, 1.f, 1.f, 1.f}; }
;         constexpr int NB = HB ? 4 : 2, MB = 4 / (NB / 2);
; #pragma unroll
;         for (int am = 0; am < NB; ++am) { const int ai = am / (NB / 2), m0 = (am % (NB / 2)) * MB;
;             f32x4 xo[4][2][2];
; #pragma unroll
;             for (int m = m0; m < m0 + MB; ++m) { const float* xr = Xs + (size_t)(row0 + ai * HALF + m * 16) * DM + col0;
; #pragma unroll
;                 for (int bj = 0; bj < 2; ++bj) { xo[m][bj][0] = *(const f32x4*)(xr + bj * HALF); xo[m][bj][1] = *(const f32x4*)(xr + bj * HALF + 4); } }
	s_add_u32 s6, s52, 0x10000
	s_addc_u32 s7, s53, 0
	s_add_i32 s50, s50, s23
	v_lshl_add_u64 v[210:211], s[6:7], 0, v[138:139]
	s_mov_b32 m0, s50
	ds_read_b128 v[164:167], v214 offset:49152
	ds_read_b128 v[168:171], v214 offset:50176
	ds_read_b128 v[172:175], v214 offset:51200
	ds_read_b128 v[176:179], v214 offset:52224
	ds_read_b128 v[188:191], v214 offset:53248
	ds_read_b128 v[206:209], v214 offset:54272
	ds_read_b128 v[216:219], v214 offset:55296
	ds_read_b128 v[220:223], v214 offset:56320
	global_load_lds_dwordx4 v[210:211], off
	s_add_i32 m0, s50, 0x2000
	v_lshl_add_u64 v[210:211], s[6:7], 0, v[136:137]
	s_add_u32 s6, s52, 0x12000
	s_addc_u32 s7, s53, 0
	s_add_i32 s50, s51, s23
	global_load_lds_dwordx4 v[210:211], off
	v_lshl_add_u64 v[210:211], s[6:7], 0, v[138:139]
	s_mov_b32 m0, s50
	v_lshl_add_u64 v[198:199], v[198:199], 0, s[36:37]
	global_load_lds_dwordx4 v[210:211], off
	v_lshl_add_u64 v[210:211], s[6:7], 0, v[136:137]
	s_add_i32 m0, s50, 0x2000
	s_nop 0
	global_load_lds_dwordx4 v[210:211], off
	s_mov_b32 m0, s59
	s_nop 0
	global_load_lds_dwordx4 v[198:199], off
	v_lshl_add_u64 v[198:199], v[200:201], 0, s[36:37]
	s_mov_b32 m0, s72
	s_nop 0
	global_load_lds_dwordx4 v[198:199], off
	s_waitcnt vmcnt(8)
	s_waitcnt lgkmcnt(0)
	s_barrier
	s_setprio 1
	s_waitcnt lgkmcnt(0)
	v_mfma_f32_16x16x32_bf16 v[60:63], v[68:71], v[164:167], v[60:63]
	v_mfma_f32_16x16x32_bf16 v[56:59], v[80:83], v[164:167], v[56:59]
	v_mfma_f32_16x16x32_bf16 v[44:47], v[68:71], v[172:175], v[44:47]
	v_mfma_f32_16x16x32_bf16 v[40:43], v[80:83], v[172:175], v[40:43]
	v_mfma_f32_16x16x32_bf16 v[28:31], v[68:71], v[188:191], v[28:31]
	v_mfma_f32_16x16x32_bf16 v[24:27], v[80:83], v[188:191], v[24:27]
	v_mfma_f32_16x16x32_bf16 v[12:15], v[68:71], v[216:219], v[12:15]
	v_mfma_f32_16x16x32_bf16 v[8:11], v[80:83], v[216:219], v[8:11]
	v_mfma_f32_16x16x32_bf16 v[60:63], v[76:79], v[168:171], v[60:63]
	v_mfma_f32_16x16x32_bf16 v[56:59], v[84:87], v[168:171], v[56:59]
	v_mfma_f32_16x16x32_bf16 v[44:47], v[76:79], v[176:179], v[44:47]
	v_mfma_f32_16x16x32_bf16 v[40:43], v[84:87], v[176:179], v[40:43]
	v_mfma_f32_16x16x32_bf16 v[28:31], v[76:79], v[206:209], v[28:31]
	v_mfma_f32_16x16x32_bf16 v[24:27], v[84:87], v[206:209], v[24:27]
	v_mfma_f32_16x16x32_bf16 v[12:15], v[76:79], v[220:223], v[12:15]
	v_mfma_f32_16x16x32_bf16 v[8:11], v[84:87], v[220:223], v[8:11]
	s_setprio 0
	s_setprio 1
	v_mfma_f32_16x16x32_bf16 v[52:55], v[88:91], v[164:167], v[52:55]
	v_mfma_f32_16x16x32_bf16 v[48:51], v[96:99], v[164:167], v[48:51]
	v_mfma_f32_16x16x32_bf16 v[36:39], v[88:91], v[172:175], v[36:39]
	v_mfma_f32_16x16x32_bf16 v[32:35], v[96:99], v[172:175], v[32:35]
	v_mfma_f32_16x16x32_bf16 v[20:23], v[88:91], v[188:191], v[20:23]
	v_mfma_f32_16x16x32_bf16 v[16:19], v[96:99], v[188:191], v[16:19]
	v_mfma_f32_16x16x32_bf16 v[4:7], v[88:91], v[216:219], v[4:7]
	v_mfma_f32_16x16x32_bf16 v[0:3], v[96:99], v[216:219], v[0:3]
	v_mfma_f32_16x16x32_bf16 v[52:55], v[92:95], v[168:171], v[52:55]
	v_mfma_f32_16x16x32_bf16 v[48:51], v[100:103], v[168:171], v[48:51]
	v_mfma_f32_16x16x32_bf16 v[36:39], v[92:95], v[176:179], v[36:39]
	v_mfma_f32_16x16x32_bf16 v[32:35], v[100:103], v[176:179], v[32:35]
	v_mfma_f32_16x16x32_bf16 v[20:23], v[92:95], v[206:209], v[20:23]
	v_mfma_f32_16x16x32_bf16 v[16:19], v[100:103], v[206:209], v[16:19]
	v_mfma_f32_16x16x32_bf16 v[4:7], v[92:95], v[220:223], v[4:7]
	v_mfma_f32_16x16x32_bf16 v[0:3], v[100:103], v[220:223], v[0:3]
	s_setprio 0
	s_barrier
	s_add_i32 s79, s79, 2
	s_add_u32 s77, s77, 0x20000
	s_addc_u32 s78, s78, 0
	s_cmp_lt_u32 s79, 6
	s_mov_b64 s[50:51], s[44:45]
	s_cbranch_scc1 .LBB0_169
	v_lshl_or_b32 v188, s12, 8, v213
	v_ashrrev_i32_e32 v189, 31, v188
	v_lshl_add_u32 v190, s13, 8, v197
	v_lshlrev_b64 v[198:199], 2, v[188:189]
	v_ashrrev_i32_e32 v191, 31, v190
	v_lshl_add_u64 v[206:207], s[82:83], 0, v[198:199]
	v_lshlrev_b64 v[200:201], 13, v[190:191]
	v_lshl_add_u64 v[68:69], s[28:29], 0, v[198:199]
	v_lshl_add_u64 v[80:81], s[46:47], 0, v[198:199]
	v_lshl_add_u64 v[164:165], v[206:207], 0, v[200:201]
	global_load_dwordx4 v[92:95], v[68:69], off offset:16
	global_load_dwordx4 v[100:103], v[68:69], off
	global_load_dwordx4 v[88:91], v[80:81], off offset:16
	global_load_dwordx4 v[96:99], v[80:81], off
	global_load_dwordx4 v[76:79], v[68:69], off offset:528
	global_load_dwordx4 v[84:87], v[68:69], off offset:512
	s_nop 0
	global_load_dwordx4 v[68:71], v[80:81], off offset:528
	s_nop 0
	global_load_dwordx4 v[80:83], v[80:81], off offset:512
	s_nop 0
	global_load_dwordx4 v[216:219], v[164:165], off offset:16
	global_load_dwordx4 v[220:223], v[164:165], off
	global_load_dwordx4 v[224:227], v[164:165], off offset:528
	global_load_dwordx4 v[228:231], v[164:165], off offset:512
	v_or_b32_e32 v208, 16, v190
	v_ashrrev_i32_e32 v209, 31, v208
	v_lshlrev_b64 v[210:211], 13, v[208:209]
	v_lshl_add_u64 v[168:169], v[206:207], 0, v[210:211]
	global_load_dwordx4 v[172:175], v[168:169], off offset:16
	global_load_dwordx4 v[176:179], v[168:169], off
	global_load_dwordx4 v[164:167], v[168:169], off offset:528
	s_nop 0
	global_load_dwordx4 v[168:171], v[168:169], off offset:512
	v_lshl_add_u64 v[200:201], s[82:83], 0, v[200:201]
	v_lshl_add_u64 v[198:199], v[200:201], 0, v[198:199]
	v_mov_b64_e32 v[200:201], s[4:5]
	v_mad_i64_i32 v[200:201], s[6:7], v190, s66, v[200:201]
	v_lshl_add_u64 v[200:201], v[188:189], 1, v[200:201]
	s_lshl_b32 s44, s12, 2
	s_ashr_i32 s45, s44, 31
	s_waitcnt vmcnt(4)
; __device__ __forceinline__ unsigned cvt_pk_bf16(float lo, float hi) { unsigned r; asm volatile("v_cvt_pk_bf16_f32 %0, %1, %2" : "=v"(r) : "v"(lo), "v"(hi)); return r; }
;     __device__ __forceinline__ void operator()(const f32x4 (&acc)[2][2][4][2], const Unit& u, int wr, int wc, int fr, int fq, const LAS float*) const {
;     ...
;         for (int am = 0; am < NB; ++am) { const int ai = am / (NB / 2), m0 = (am % (NB / 2)) * MB;
;             f32x4 xo[4][2][2];
; #pragma unroll
;             for (int m = m0; m < m0 + MB; ++m) { const float* xr = Xs + (size_t)(row0 + ai * HALF + m * 16) * DM + col0;
; #pragma unroll
;                 for (int bj = 0; bj < 2; ++bj) { xo[m][bj][0] = *(const f32x4*)(xr + bj * HALF); xo[m][bj][1] = *(const f32x4*)(xr + bj * HALF + 4); } }
; #pragma unroll
;             for (int m = m0; m < m0 + MB; ++m) { const int row = row0 + ai * HALF + m * 16; float ss = 0.f;
;                 float* xr = X + (size_t)row * DM + col0; bf16_t* xb = XB + (size_t)row * ALD + col0;
; #pragma unroll
;                 for (int bj = 0; bj < 2; ++bj) { f32x4 x0 = xo[m][bj][0], x1 = xo[m][bj][1];
;                     if (HB) { x0 += (acc[ai][bj][m][0] + bv[bj][0]) * sv[bj][0]; x1 += (acc[ai][bj][m][1] + bv[bj][1]) * sv[bj][1]; } else { x0 += acc[ai][bj][m][0]; x1 += acc[ai][bj][m][1]; }
;                     *(f32x4*)(xr + bj * HALF) = x0; *(f32x4*)(xr + bj * HALF + 4) = x1;
;                     ss += (x0[0] * x0[0] + x0[1] * x0[1]) + (x0[2] * x0[2] + x0[3] * x0[3]) + (x1[0] * x1[0] + x1[1] * x1[1]) + (x1[2] * x1[2] + x1[3] * x1[3]);
;                     u32x4 w; w.x = cvt_pk_bf16(x0[0], x0[1]); w.y = cvt_pk_bf16(x0[2], x0[3]); w.z = cvt_pk_bf16(x1[0], x1[1]); w.w = cvt_pk_bf16(x1[2], x1[3]);
;                     if (feeds) *(u32x4*)(xb + bj * HALF) = w; }
;                 ss += __shfl_xor(ss, 16); ss += __shfl_xor(ss, 32);
;                 if (fq == 0 && feeds) part[(size_t)row * NPART + u.pn * 4 + wc] = ss; }
	v_pk_add_f32 v[156:157], v[156:157], v[92:93]
	v_pk_add_f32 v[162:163], v[162:163], v[102:103]
	v_pk_add_f32 v[160:161], v[160:161], v[100:101]
	v_pk_add_f32 v[158:159], v[158:159], v[94:95]
	v_pk_add_f32 v[148:149], v[148:149], v[76:77]
	v_pk_fma_f32 v[156:157], v[88:89], v[156:157], v[216:217]
	v_pk_fma_f32 v[162:163], v[98:99], v[162:163], v[222:223]
	v_pk_fma_f32 v[160:161], v[96:97], v[160:161], v[220:221]
	v_mul_f32_e32 v216, v163, v163
	v_mul_f32_e32 v215, v161, v161
	v_fmac_f32_e32 v215, v160, v160
	v_fmac_f32_e32 v216, v162, v162
	v_pk_add_f32 v[154:155], v[154:155], v[86:87]
	v_pk_add_f32 v[152:153], v[152:153], v[84:85]
	v_add_f32_e32 v215, v215, v216
	v_mul_f32_e32 v216, v157, v157
	v_pk_fma_f32 v[154:155], v[82:83], v[154:155], v[230:231]
	v_pk_fma_f32 v[152:153], v[80:81], v[152:153], v[228:229]
	v_pk_fma_f32 v[158:159], v[90:91], v[158:159], v[218:219]
	global_store_dwordx4 v[198:199], v[160:163], off
	global_store_dwordx4 v[198:199], v[156:159], off offset:16
	v_fmac_f32_e32 v216, v156, v156
	v_cvt_pk_bf16_f32 v160, v160, v161
	v_cvt_pk_bf16_f32 v161, v162, v163
	v_cvt_pk_bf16_f32 v162, v156, v157
	v_pk_fma_f32 v[148:149], v[68:69], v[148:149], v[224:225]
	v_mul_f32_e32 v156, v153, v153
	v_mul_f32_e32 v157, v155, v155
	v_fmac_f32_e32 v156, v152, v152
	v_fmac_f32_e32 v157, v154, v154
	v_pk_add_f32 v[150:151], v[150:151], v[78:79]
	v_add_f32_e32 v156, v156, v157
	v_mul_f32_e32 v157, v149, v149
	v_cvt_pk_bf16_f32 v163, v158, v159
	global_store_dwordx4 v[200:201], v[160:163], off
	v_pk_fma_f32 v[150:151], v[70:71], v[150:151], v[226:227]
	global_store_dwordx4 v[198:199], v[152:155], off offset:512
	global_store_dwordx4 v[198:199], v[148:151], off offset:528
	v_fmac_f32_e32 v157, v148, v148
	v_cvt_pk_bf16_f32 v152, v152, v153
	v_cvt_pk_bf16_f32 v153, v154, v155
	v_cvt_pk_bf16_f32 v154, v148, v149
	v_add_f32_e32 v215, v215, v216
	v_and_b32_e32 v149, 64, v239
	v_mul_f32_e32 v216, v159, v159
	v_add_f32_e32 v156, v156, v157
	v_mul_f32_e32 v157, v151, v151
	v_xor_b32_e32 v148, 16, v239
	v_add_u32_e32 v149, 64, v149
	v_fmac_f32_e32 v216, v158, v158
	v_fmac_f32_e32 v157, v150, v150
	v_cmp_lt_i32_e32 vcc, v148, v149
	v_add_f32_e32 v215, v216, v215
	v_add_f32_e32 v156, v157, v156
	v_cndmask_b32_e32 v148, v239, v148, vcc
	v_add_f32_e32 v156, v215, v156
	v_cvt_pk_bf16_f32 v155, v150, v151
	global_store_dwordx4 v[200:201], v[152:155], off offset:256
	v_xor_b32_e32 v150, 32, v239
	v_cmp_lt_i32_e32 vcc, v150, v149
	v_lshlrev_b32_e32 v154, 2, v148
	ds_bpermute_b32 v148, v154, v156
	v_cndmask_b32_e32 v149, v239, v150, vcc
	v_lshlrev_b32_e32 v155, 2, v149
	s_waitcnt lgkmcnt(0)
	v_add_f32_e32 v148, v156, v148
	ds_bpermute_b32 v149, v155, v148
	s_and_saveexec_b64 s[50:51], s[38:39]
	s_cbranch_execz .LBB0_172
	v_lshlrev_b64 v[150:151], 7, v[190:191]
	v_lshl_add_u64 v[150:151], s[94:95], 0, v[150:151]
	v_lshl_add_u64 v[150:151], s[44:45], 2, v[150:151]
	s_lshl_b32 s30, s58, 2
	v_lshl_add_u64 v[150:151], v[150:151], 0, s[30:31]
	s_waitcnt lgkmcnt(0)
	v_add_f32_e32 v148, v148, v149
	global_store_dword v[150:151], v148, off
.LBB0_172:
	s_or_b64 exec, exec, s[50:51]
	s_waitcnt vmcnt(6)
	v_pk_add_f32 v[146:147], v[146:147], v[102:103]
	v_pk_add_f32 v[144:145], v[144:145], v[100:101]
	v_pk_fma_f32 v[146:147], v[98:99], v[146:147], v[178:179]
	v_pk_fma_f32 v[144:145], v[96:97], v[144:145], v[176:177]
	v_pk_add_f32 v[140:141], v[140:141], v[92:93]
	v_mul_f32_e32 v152, v145, v145
	v_mul_f32_e32 v153, v147, v147
	s_waitcnt lgkmcnt(0)
	v_lshl_add_u64 v[148:149], s[82:83], 0, v[210:211]
	v_pk_fma_f32 v[140:141], v[88:89], v[140:141], v[172:173]
	v_fmac_f32_e32 v152, v144, v144
	v_fmac_f32_e32 v153, v146, v146
	v_pk_add_f32 v[134:135], v[134:135], v[86:87]
	v_pk_add_f32 v[132:133], v[132:133], v[84:85]
	v_lshl_add_u64 v[148:149], v[188:189], 2, v[148:149]
	v_pk_add_f32 v[142:143], v[142:143], v[94:95]
	v_add_f32_e32 v152, v152, v153
	v_mul_f32_e32 v153, v141, v141
	v_pk_fma_f32 v[134:135], v[82:83], v[134:135], v[170:171]
	v_pk_fma_f32 v[132:133], v[80:81], v[132:133], v[168:169]
	v_pk_add_f32 v[128:129], v[128:129], v[76:77]
	v_pk_fma_f32 v[142:143], v[90:91], v[142:143], v[174:175]
	global_store_dwordx4 v[148:149], v[144:147], off
	global_store_dwordx4 v[148:149], v[140:143], off offset:16
	v_fmac_f32_e32 v153, v140, v140
	v_cvt_pk_bf16_f32 v144, v144, v145
	v_cvt_pk_bf16_f32 v145, v146, v147
	v_cvt_pk_bf16_f32 v146, v140, v141
	v_add_f32_e32 v152, v152, v153
	v_pk_fma_f32 v[140:141], v[68:69], v[128:129], v[164:165]
	v_mul_f32_e32 v128, v133, v133
	v_mul_f32_e32 v129, v135, v135
	v_fmac_f32_e32 v128, v132, v132
	v_fmac_f32_e32 v129, v134, v134
	v_mul_f32_e32 v153, v143, v143
	v_pk_add_f32 v[130:131], v[130:131], v[78:79]
	v_add_f32_e32 v128, v128, v129
	v_mul_f32_e32 v129, v141, v141
	v_fmac_f32_e32 v153, v142, v142
	v_cvt_pk_bf16_f32 v147, v142, v143
	v_pk_fma_f32 v[142:143], v[70:71], v[130:131], v[166:167]
	v_fmac_f32_e32 v129, v140, v140
	v_add_f32_e32 v128, v128, v129
	v_mul_f32_e32 v129, v143, v143
	v_fmac_f32_e32 v129, v142, v142
	v_add_f32_e32 v152, v153, v152
	v_add_f32_e32 v128, v129, v128
	v_add_f32_e32 v128, v152, v128
	ds_bpermute_b32 v129, v154, v128
	v_mov_b64_e32 v[150:151], s[4:5]
	v_mad_i64_i32 v[150:151], s[6:7], v208, s66, v[150:151]
	v_lshl_add_u64 v[150:151], v[188:189], 1, v[150:151]
	s_waitcnt lgkmcnt(0)
	v_add_f32_e32 v128, v128, v129
	ds_bpermute_b32 v129, v155, v128
	global_store_dwordx4 v[150:151], v[144:147], off
	global_store_dwordx4 v[148:149], v[132:135], off offset:512
	global_store_dwordx4 v[148:149], v[140:143], off offset:528
	v_cvt_pk_bf16_f32 v130, v132, v133
	v_cvt_pk_bf16_f32 v131, v134, v135
	s_nop 0
	v_cvt_pk_bf16_f32 v132, v140, v141
	v_cvt_pk_bf16_f32 v133, v142, v143
	global_store_dwordx4 v[150:151], v[130:133], off offset:256
	s_and_saveexec_b64 s[50:51], s[38:39]
	s_cbranch_execz .LBB0_174
	v_lshlrev_b64 v[130:131], 7, v[208:209]
	v_lshl_add_u64 v[130:131], s[94:95], 0, v[130:131]
	v_lshl_add_u64 v[130:131], s[44:45], 2, v[130:131]
	s_lshl_b32 s30, s58, 2
	v_lshl_add_u64 v[130:131], v[130:131], 0, s[30:31]
	s_waitcnt lgkmcnt(0)
	v_add_f32_e32 v128, v128, v129
	global_store_dword v[130:131], v128, off

; template <class Epi, bool ALIGN_EPI>
; __device__ __forceinline__ void gemm_phase(LAS unsigned char* lds, const Gemm g, int G, int cid, const Epi& E) {
;     ...
;         const bool has_next = S.next(ui + 1, nxt);
;         const char* nA = has_next ? tileA(g, nxt) : cA; const char* nB = has_next ? tileB(g, nxt) : cB;
;     ...
; #pragma unroll
;         for (int a = 0; a < 2; ++a)
; #pragma unroll
;             for (int b = 0; b < 2; ++b)
; #pragma unroll
;                 for (int m = 0; m < 4; ++m)
; #pragma unroll
;                     for (int n = 0; n < 2; ++n) acc[a][b][m][n] = (f32x4){0.f, 0.f, 0.f, 0.f};
;         cur = nxt; cA = nA; cB = nB; ++ui;
.LBB0_726:
	s_and_b32 s30, s72, 0x7fffffff
	s_lshl_b64 s[44:45], s[30:31], 14
	s_add_u32 s44, s1, s44
	s_addc_u32 s45, s24, s45
	s_and_b64 s[42:43], s[42:43], exec
	s_cselect_b32 s30, s45, s49
	s_cselect_b32 s74, s44, s48
	s_add_u32 s75, s48, 0x80000
	v_mov_b32_e32 v0, 0
	s_addc_u32 s76, s49, 0
	s_mov_b32 s77, -2
	s_waitcnt lgkmcnt(0)
	v_mov_b32_e32 v1, v0
	v_mov_b32_e32 v2, v0
	v_mov_b32_e32 v3, v0
	v_mov_b32_e32 v4, v0
	v_mov_b32_e32 v5, v0
	v_mov_b32_e32 v6, v0
	v_mov_b32_e32 v7, v0
	v_mov_b32_e32 v16, v0
	v_mov_b32_e32 v17, v0
	v_mov_b32_e32 v18, v0
	v_mov_b32_e32 v19, v0
	v_mov_b32_e32 v20, v0
	v_mov_b32_e32 v21, v0
	v_mov_b32_e32 v22, v0
	v_mov_b32_e32 v23, v0
	v_mov_b32_e32 v32, v0
	v_mov_b32_e32 v33, v0
	v_mov_b32_e32 v34, v0
	v_mov_b32_e32 v35, v0
	v_mov_b32_e32 v36, v0
	v_mov_b32_e32 v37, v0
	v_mov_b32_e32 v38, v0
	v_mov_b32_e32 v39, v0
	v_mov_b32_e32 v48, v0
	v_mov_b32_e32 v49, v0
	v_mov_b32_e32 v50, v0
	v_mov_b32_e32 v51, v0
	v_mov_b32_e32 v52, v0
	v_mov_b32_e32 v53, v0
	v_mov_b32_e32 v54, v0
	v_mov_b32_e32 v55, v0
	v_mov_b32_e32 v8, v0
	v_mov_b32_e32 v9, v0
	v_mov_b32_e32 v10, v0
	v_mov_b32_e32 v11, v0
	v_mov_b32_e32 v12, v0
	v_mov_b32_e32 v13, v0
	v_mov_b32_e32 v14, v0
	v_mov_b32_e32 v15, v0
	v_mov_b32_e32 v24, v0
	v_mov_b32_e32 v25, v0
	v_mov_b32_e32 v26, v0
	v_mov_b32_e32 v27, v0
	v_mov_b32_e32 v28, v0
	v_mov_b32_e32 v29, v0
	v_mov_b32_e32 v30, v0
	v_mov_b32_e32 v31, v0
	v_mov_b32_e32 v40, v0
	v_mov_b32_e32 v41, v0
	v_mov_b32_e32 v42, v0
	v_mov_b32_e32 v43, v0
	v_mov_b32_e32 v44, v0
	v_mov_b32_e32 v45, v0
	v_mov_b32_e32 v46, v0
	v_mov_b32_e32 v47, v0
	v_mov_b32_e32 v56, v0
	v_mov_b32_e32 v57, v0
	v_mov_b32_e32 v58, v0
	v_mov_b32_e32 v59, v0
	v_mov_b32_e32 v60, v0
	v_mov_b32_e32 v61, v0
	v_mov_b32_e32 v62, v0
	v_mov_b32_e32 v63, v0
	v_mov_b32_e32 v64, v0
	v_mov_b32_e32 v65, v0
	v_mov_b32_e32 v66, v0
	v_mov_b32_e32 v67, v0
	v_mov_b32_e32 v68, v0
	v_mov_b32_e32 v69, v0
	v_mov_b32_e32 v70, v0
	v_mov_b32_e32 v71, v0
	v_mov_b32_e32 v80, v0
	v_mov_b32_e32 v81, v0
	v_mov_b32_e32 v82, v0
	v_mov_b32_e32 v83, v0
	v_mov_b32_e32 v84, v0
	v_mov_b32_e32 v85, v0
	v_mov_b32_e32 v86, v0
	v_mov_b32_e32 v87, v0
	v_mov_b32_e32 v96, v0
	v_mov_b32_e32 v97, v0
	v_mov_b32_e32 v98, v0
	v_mov_b32_e32 v99, v0
	v_mov_b32_e32 v100, v0
	v_mov_b32_e32 v101, v0
	v_mov_b32_e32 v102, v0
	v_mov_b32_e32 v103, v0
	v_mov_b32_e32 v120, v0
	v_mov_b32_e32 v121, v0
	v_mov_b32_e32 v122, v0
	v_mov_b32_e32 v123, v0
	v_mov_b32_e32 v124, v0
	v_mov_b32_e32 v125, v0
	v_mov_b32_e32 v126, v0
	v_mov_b32_e32 v127, v0
	v_mov_b32_e32 v72, v0
	v_mov_b32_e32 v73, v0
	v_mov_b32_e32 v74, v0
	v_mov_b32_e32 v75, v0
	v_mov_b32_e32 v76, v0
	v_mov_b32_e32 v77, v0
	v_mov_b32_e32 v78, v0
	v_mov_b32_e32 v79, v0
	v_mov_b32_e32 v88, v0
	v_mov_b32_e32 v89, v0
	v_mov_b32_e32 v90, v0
	v_mov_b32_e32 v91, v0
	v_mov_b32_e32 v92, v0
	v_mov_b32_e32 v93, v0
	v_mov_b32_e32 v94, v0
	v_mov_b32_e32 v95, v0
	v_mov_b32_e32 v104, v0
	v_mov_b32_e32 v105, v0
	v_mov_b32_e32 v106, v0
	v_mov_b32_e32 v107, v0
	v_mov_b32_e32 v108, v0
	v_mov_b32_e32 v109, v0
	v_mov_b32_e32 v110, v0
	v_mov_b32_e32 v111, v0
	v_mov_b32_e32 v148, v0
	v_mov_b32_e32 v149, v0
	v_mov_b32_e32 v150, v0
	v_mov_b32_e32 v151, v0
	v_mov_b32_e32 v152, v0
	v_mov_b32_e32 v153, v0
	v_mov_b32_e32 v154, v0
	v_mov_b32_e32 v155, v0
	v_mbcnt_lo_u32_b32 v224, -1, 0
	v_mbcnt_hi_u32_b32 v224, -1, v224
	v_lshlrev_b32_e32 v224, 4, v224
